# attention: V^T LDS tile stored in P k-slot order with a row XOR swizzle so each P.V fragment is one conflict-free ds_read_b128 (was bank-conflicted ds_read2_b64)
# speedup vs baseline: 1.0327x; 1.0168x over previous
.LBB0_1054:
	s_or_b64 exec, exec, s[4:5]
	v_mov_b32_e32 v0, s48
	s_waitcnt lgkmcnt(0)
	s_barrier
	ds_read_b32 v0, v0
	s_waitcnt lgkmcnt(0)
	v_cmp_lt_i32_e32 vcc, 63, v0
	v_readfirstlane_b32 s4, v0
	s_cbranch_vccnz .LBB0_1073
	s_mov_b64 s[82:83], s[0:1]
	v_mov_b32_e32 v100, v226
	s_load_dwordx2 s[50:51], s[82:83], 0x58
	s_and_b32 s5, s4, 1
	s_lshl_b32 s4, s4, 1
	s_and_b32 s4, s4, -4
	v_readlane_b32 s6, v254, 14
	s_sub_i32 s4, 0x7c, s4
	s_or_b32 s6, s5, s6
	v_readlane_b32 s5, v254, 13
	s_or_b32 s5, s4, s5
	s_waitcnt lgkmcnt(0)
	s_add_u32 s56, s50, 0xb400000
	s_addc_u32 s57, s51, 0
	s_bfe_u32 s9, s4, 0x50002
	v_readfirstlane_b32 s4, v100
	s_ashr_i32 s7, s4, 8
	s_lshl_b32 s22, s6, 1
	s_add_i32 s8, s7, s22
	v_and_b32_e32 v28, 15, v100
	s_lshl_b32 s5, s5, 4
	s_lshr_b32 s4, s4, 2
	s_lshl_b32 s8, s8, 7
	s_and_b32 s23, s5, 0xfffff800
	s_lshl_b32 s5, s9, 6
	v_and_or_b32 v127, s4, 48, v28
	s_add_i32 s4, s8, 0x800
	s_or_b32 s5, s5, s23
	s_ashr_i32 s4, s4, 7
	v_or_b32_e32 v96, s5, v127
	s_ashr_i32 s5, s4, 31
	s_lshl_b64 s[4:5], s[4:5], 21
	v_ashrrev_i32_e32 v18, 5, v100
	v_ashrrev_i32_e32 v97, 31, v96
	s_add_u32 s4, s56, s4
	v_add_u32_e32 v16, s23, v18
	v_bfe_u32 v29, v100, 4, 2
	s_addc_u32 s5, s57, s5
	v_lshlrev_b64 v[98:99], 8, v[96:97]
	v_ashrrev_i32_e32 v17, 31, v16
	v_lshl_add_u64 v[0:1], s[4:5], 0, v[98:99]
	v_lshlrev_b32_e32 v208, 4, v29
	v_and_b32_e32 v19, 16, v100
	v_lshlrev_b64 v[16:17], 8, v[16:17]
	s_lshl_b32 s4, s6, 22
	v_lshl_add_u64 v[12:13], v[0:1], 0, v[208:209]
	v_lshl_add_u64 v[16:17], s[56:57], 0, v[16:17]
	v_lshl_or_b32 v208, v19, 17, s4
	v_lshlrev_b32_e32 v19, 4, v100
	v_lshl_add_u64 v[16:17], v[16:17], 0, v[208:209]
	v_and_b32_e32 v208, 0xf0, v19
	v_lshl_add_u64 v[16:17], v[16:17], 0, v[208:209]
	v_ashrrev_i32_e32 v19, 3, v100
	s_ashr_i32 s4, s23, 6
	v_lshl_add_u64 v[102:103], v[16:17], 0, s[62:63]
	v_lshl_add_u32 v16, s6, 8, v19
	s_ashr_i32 s5, s4, 31
	v_add_u32_e32 v16, 0x400, v16
	s_lshl_b64 s[4:5], s[4:5], 18
	v_lshlrev_b32_e32 v21, 3, v100
	v_ashrrev_i32_e32 v17, 31, v16
	s_add_u32 s4, s50, s4
	v_and_b32_e32 v22, 56, v21
	s_addc_u32 s5, s51, s5
	v_lshlrev_b64 v[16:17], 7, v[16:17]
	v_lshl_add_u64 v[16:17], s[4:5], 0, v[16:17]
	v_lshlrev_b32_e32 v208, 1, v22
	v_lshl_add_u64 v[16:17], v[16:17], 0, v[208:209]
	v_lshl_add_u64 v[104:105], v[16:17], 0, s[64:65]
	v_mul_lo_u32 v16, v19, s49
	v_add_lshl_u32 v31, v16, v22, 1
	v_lshlrev_b32_e32 v16, 2, v100
	v_sub_u32_e64 v20, s9, 8 clamp
	v_and_b32_e32 v16, 64, v16
	v_add_u32_e32 v16, v16, v18
	v_lshlrev_b32_e32 v208, 18, v20
	v_mul_lo_u32 v56, v16, s28
	v_lshl_add_u64 v[16:17], v[104:105], 0, v[208:209]
	v_add_co_u32_e32 v18, vcc, s21, v16
	v_lshlrev_b32_e32 v208, 14, v20
	v_readfirstlane_b32 s31, v20
	v_and_b32_e32 v57, 0x78, v21
	v_addc_co_u32_e32 v19, vcc, 0, v17, vcc
	v_lshl_add_u64 v[20:21], v[102:103], 0, v[208:209]
	v_add_co_u32_e32 v22, vcc, s35, v20
	global_load_dwordx4 v[0:3], v[12:13], off
	global_load_dwordx4 v[4:7], v[12:13], off offset:64
	global_load_dwordx4 v[8:11], v[12:13], off offset:128
	s_nop 0
	global_load_dwordx4 v[12:15], v[12:13], off offset:192
	v_addc_co_u32_e32 v23, vcc, 0, v21, vcc
	v_add_co_u32_e32 v24, vcc, s20, v16
	s_mul_i32 s4, s7, 0x410
	s_nop 0
	v_addc_co_u32_e32 v25, vcc, 0, v17, vcc
	v_add_co_u32_e32 v26, vcc, s17, v20
	s_add_i32 s38, s4, 0
	s_nop 0
	v_addc_co_u32_e32 v27, vcc, 0, v21, vcc
	global_load_dwordx4 v[52:55], v[24:25], off
	global_load_dwordx4 v[48:51], v[26:27], off
	v_add_co_u32_e32 v24, vcc, s17, v16
	v_lshlrev_b32_e32 v30, 3, v29
	s_nop 0
	v_addc_co_u32_e32 v25, vcc, 0, v17, vcc
	v_add_co_u32_e32 v26, vcc, s34, v20
	s_or_b32 s84, s12, s22
	s_nop 0
	v_addc_co_u32_e32 v27, vcc, 0, v21, vcc
	global_load_dwordx4 v[44:47], v[24:25], off
	global_load_dwordx4 v[40:43], v[26:27], off
	global_load_dwordx4 v[64:67], v[18:19], off
	global_load_dwordx4 v[32:35], v[16:17], off
	global_load_dwordx4 v[60:63], v[22:23], off
	global_load_dwordx4 v[36:39], v[20:21], off
	v_and_b32_e32 v19, 64, v233
	v_xor_b32_e32 v18, 16, v233
	v_add_u32_e32 v19, 64, v19
	v_cmp_lt_i32_e64 s[4:5], v18, v19
	v_max_i32_e32 v20, 2, v100
	v_sub_u32_e32 v20, v20, v100
	v_cndmask_b32_e64 v18, v233, v18, s[4:5]
	v_lshlrev_b32_e32 v126, 2, v18
	v_xor_b32_e32 v18, 32, v233
	v_cmp_lt_i32_e64 s[4:5], v18, v19
	v_add_u32_e32 v20, 0x1ff, v20
	v_lshl_or_b32 v17, s7, 6, v28
	v_cndmask_b32_e64 v18, v233, v18, s[4:5]
	v_lshrrev_b32_e32 v21, 9, v20
	v_mul_lo_u32 v17, v17, s28
	v_lshlrev_b32_e32 v125, 2, v18
	v_lshl_or_b32 v18, s7, 7, v28
	v_add_u32_e32 v21, 1, v21
	v_add_lshl_u32 v16, v56, v57, 1
	v_cmp_lt_i32_e32 vcc, s24, v100
	v_add_lshl_u32 v17, v17, v30, 1
	v_mul_lo_u32 v18, v18, s16
	v_add_u32_e32 v19, 0, v30
	v_lshlrev_b32_e32 v208, 2, v29
	v_and_b32_e32 v129, 0xfffffe, v21
	v_mov_b32_e32 v135, 0
	s_mov_b32 s42, s76
	s_add_i32 s38, s38, 0x16000
	s_mov_b32 s85, s13
	v_not_b32_e32 v128, v208
	v_or_b32_e32 v124, 16, v208
	v_or_b32_e32 v123, 32, v208
	v_or_b32_e32 v122, 48, v208
	v_cmp_lt_u32_e64 s[4:5], s61, v20
	v_lshl_add_u32 v130, v129, 9, v100
	s_mov_b32 s86, s84
	s_mov_b32 s87, s13
	s_mov_b32 s88, s84
	s_mov_b32 s89, s13
	v_add_u32_e32 v101, 0x200, v100
	v_cmp_ne_u32_e64 s[6:7], v21, v129
	v_mov_b32_e32 v136, 0xf149f2ca
	v_add_u32_e32 v131, 0, v16
	v_add_u32_e32 v132, 0, v31
	s_xor_b64 s[90:91], vcc, -1
	v_add_u32_e32 v133, 0, v17
	v_add_u32_e32 v134, v19, v18
	v_and_b32_e32 v149, 15, v100
	v_add_u32_e32 v149, 4, v149
	v_bfe_u32 v149, v149, 3, 1
	v_bfe_u32 v150, v100, 4, 2
	v_xor_b32_e32 v151, v150, v149
	v_lshlrev_b32_e32 v151, 4, v151
	v_lshlrev_b32_e32 v150, 3, v150
	v_sub_u32_e32 v151, v151, v150
	v_add_u32_e32 v134, v134, v151
	v_and_b32_e32 v149, 7, v100
	v_lshlrev_b32_e32 v150, 4, v149
	v_sub_u32_e32 v132, v132, v150
	v_and_b32_e32 v150, 4, v149
	v_lshl_add_u32 v132, v150, 4, v132
	v_and_b32_e32 v150, 1, v149
	v_lshl_add_u32 v132, v150, 5, v132
	v_and_b32_e32 v150, 2, v149
	v_lshl_add_u32 v132, v150, 2, v132
	v_bfe_u32 v150, v100, 3, 4
	v_add_u32_e32 v150, 4, v150
	v_bfe_u32 v150, v150, 3, 1
	v_lshlrev_b32_e32 v150, 4, v150
	v_sub_u32_e32 v148, 16, v150
	v_add_u32_e32 v148, v148, v132
	v_add_u32_e32 v132, v132, v150
	s_mov_b32 s39, s31
	v_mov_b32_e32 v20, 0
	v_mov_b32_e32 v21, v135
	v_mov_b32_e32 v22, v135
	v_mov_b32_e32 v23, v135
	v_mov_b32_e32 v28, 0
	v_mov_b32_e32 v29, v135
	v_mov_b32_e32 v30, v135
	v_mov_b32_e32 v31, v135
	v_mov_b32_e32 v16, 0
	v_mov_b32_e32 v17, v135
	v_mov_b32_e32 v18, v135
	v_mov_b32_e32 v19, v135
	v_mov_b32_e32 v56, 0
	v_mov_b32_e32 v57, v135
	v_mov_b32_e32 v58, v135
	v_mov_b32_e32 v59, v135
	v_mov_b32_e32 v68, 0
	v_mov_b32_e32 v69, v135
	v_mov_b32_e32 v70, v135
	v_mov_b32_e32 v71, v135
	v_mov_b32_e32 v72, 0
	v_mov_b32_e32 v73, v135
	v_mov_b32_e32 v74, v135
	v_mov_b32_e32 v75, v135
	v_mov_b32_e32 v24, 0
	v_mov_b32_e32 v25, v135
	v_mov_b32_e32 v26, v135
	v_mov_b32_e32 v27, v135
	v_mov_b32_e32 v76, 0
	v_mov_b32_e32 v77, v135
	v_mov_b32_e32 v78, v135
	v_mov_b32_e32 v79, v135
.LBB0_1056:
	s_cmp_eq_u32 s39, s31
	s_cselect_b64 s[22:23], -1, 0
	s_and_b64 s[22:23], s[90:91], s[22:23]
	s_barrier
	s_waitcnt vmcnt(0)
	ds_write_b128 v131, v[36:39]
	ds_write_b64 v132, v[32:33] offset:34816
	ds_write_b64 v148, v[34:35] offset:34816
	ds_write_b128 v131, v[40:43] offset:4352
	ds_write_b64 v132, v[44:45] offset:44032
	ds_write_b64 v148, v[46:47] offset:44032
	ds_write_b128 v131, v[48:51] offset:8704
	ds_write_b64 v132, v[52:53] offset:53248
	ds_write_b64 v148, v[54:55] offset:53248
	ds_write_b128 v131, v[60:63] offset:13056
	ds_write_b64 v132, v[64:65] offset:62464
	ds_write_b64 v148, v[66:67] offset:62464
	s_and_saveexec_b64 s[76:77], s[22:23]
	s_cbranch_execz .LBB0_1064
	s_load_dwordx2 s[92:93], s[82:83], 0x48
	s_mov_b64 s[22:23], -1
	v_mov_b32_e32 v80, v100
	s_and_saveexec_b64 s[94:95], s[4:5]
	s_cbranch_execz .LBB0_1061
	s_mov_b64 s[96:97], 0
	v_mov_b32_e32 v82, v129
	v_mov_b64_e32 v[80:81], v[100:101]

.LBB0_1070:
	s_nop 1
	ds_bpermute_b32 v80, v126, v137
	v_max_f32_e32 v81, v137, v137
	s_waitcnt lgkmcnt(0)
	v_max_f32_e32 v80, v80, v80
	v_max_f32_e32 v80, v81, v80
	ds_bpermute_b32 v81, v125, v80
	s_waitcnt lgkmcnt(0)
	v_max3_f32 v88, v136, v80, v81
	v_sub_f32_e32 v80, v136, v88
	v_exp_f32_e32 v90, v80
	v_sub_f32_e32 v80, v120, v88
	v_exp_f32_e32 v80, v80
	v_sub_f32_e32 v82, v121, v88
	v_exp_f32_e32 v82, v82
	v_sub_f32_e32 v83, v112, v88
	v_exp_f32_e32 v83, v83
	v_sub_f32_e32 v84, v113, v88
	v_exp_f32_e32 v84, v84
	v_sub_f32_e32 v85, v108, v88
	v_fma_f32 v81, v135, v90, v80
	v_exp_f32_e32 v85, v85
	v_sub_f32_e32 v86, v109, v88
	v_add_f32_e32 v81, v82, v81
	v_exp_f32_e32 v86, v86
	v_sub_f32_e32 v87, v106, v88
	v_add_f32_e32 v81, v83, v81
	v_exp_f32_e32 v87, v87
	v_sub_f32_e32 v89, v107, v88
	v_add_f32_e32 v81, v84, v81
	v_exp_f32_e32 v89, v89
	v_add_f32_e32 v81, v85, v81
	v_add_f32_e32 v81, v86, v81
	v_add_f32_e32 v81, v87, v81
	v_add_f32_e32 v91, v89, v81
	v_cvt_pk_bf16_f32 v81, v83, v84
	v_sub_f32_e32 v84, v110, v88
	v_cvt_pk_bf16_f32 v83, v87, v89
	v_exp_f32_e32 v89, v84
	v_sub_f32_e32 v84, v111, v88
	v_exp_f32_e32 v92, v84
	v_sub_f32_e32 v84, v114, v88
	v_exp_f32_e32 v93, v84
	v_sub_f32_e32 v84, v115, v88
	v_exp_f32_e32 v94, v84
	v_sub_f32_e32 v84, v116, v88
	v_exp_f32_e32 v95, v84
	v_sub_f32_e32 v84, v117, v88
	v_exp_f32_e32 v106, v84
	v_sub_f32_e32 v84, v118, v88
	v_exp_f32_e32 v107, v84
	v_sub_f32_e32 v84, v119, v88
	v_exp_f32_e32 v135, v84
	v_cvt_pk_bf16_f32 v84, v89, v92
	v_add_f32_e32 v89, v89, v91
	v_add_f32_e32 v89, v92, v89
	v_add_f32_e32 v89, v93, v89
	v_add_f32_e32 v89, v94, v89
	v_add_f32_e32 v89, v95, v89
	v_cvt_pk_bf16_f32 v80, v80, v82
	v_cvt_pk_bf16_f32 v82, v85, v86
	v_cvt_pk_bf16_f32 v85, v93, v94
	v_add_f32_e32 v89, v106, v89
	v_add_u32_e32 v94, 0x8800, v134
	v_cvt_pk_bf16_f32 v86, v95, v106
	v_cvt_pk_bf16_f32 v87, v107, v135
	v_pk_mul_f32 v[74:75], v[74:75], v[90:91] op_sel_hi:[1,0]
	v_pk_mul_f32 v[72:73], v[72:73], v[90:91] op_sel_hi:[1,0]
	v_pk_mul_f32 v[70:71], v[70:71], v[90:91] op_sel_hi:[1,0]
	v_pk_mul_f32 v[68:69], v[68:69], v[90:91] op_sel_hi:[1,0]
	v_pk_mul_f32 v[58:59], v[58:59], v[90:91] op_sel_hi:[1,0]
	v_pk_mul_f32 v[56:57], v[56:57], v[90:91] op_sel_hi:[1,0]
	v_pk_mul_f32 v[18:19], v[18:19], v[90:91] op_sel_hi:[1,0]
	v_pk_mul_f32 v[16:17], v[16:17], v[90:91] op_sel_hi:[1,0]
	v_pk_mul_f32 v[30:31], v[30:31], v[90:91] op_sel_hi:[1,0]
	v_pk_mul_f32 v[28:29], v[28:29], v[90:91] op_sel_hi:[1,0]
	v_pk_mul_f32 v[22:23], v[22:23], v[90:91] op_sel_hi:[1,0]
	v_pk_mul_f32 v[20:21], v[20:21], v[90:91] op_sel_hi:[1,0]
	v_pk_mul_f32 v[26:27], v[26:27], v[90:91] op_sel_hi:[1,0]
	v_pk_mul_f32 v[24:25], v[24:25], v[90:91] op_sel_hi:[1,0]
	v_pk_mul_f32 v[78:79], v[78:79], v[90:91] op_sel_hi:[1,0]
	v_pk_mul_f32 v[76:77], v[76:77], v[90:91] op_sel_hi:[1,0]
	v_add_f32_e32 v89, v107, v89
	ds_read_b128 v[90:93], v94
	ds_read_b128 v[106:109], v94 offset:64
	v_add_u32_e32 v94, 0x9000, v134
	ds_read_b128 v[110:113], v94 offset:256
	ds_read_b128 v[114:117], v94 offset:320
	v_add_u32_e32 v94, 0x9800, v134
	ds_read_b128 v[118:121], v94 offset:512
	ds_read_b128 v[136:139], v94 offset:576
	v_add_u32_e32 v94, 0xa000, v134
	ds_read_b128 v[140:143], v94 offset:768
	ds_read_b128 v[144:147], v94 offset:832
	s_waitcnt lgkmcnt(7)
	v_mfma_f32_16x16x32_bf16 v[72:75], v[90:93], v[80:83], v[72:75]
	s_waitcnt lgkmcnt(5)
	v_mfma_f32_16x16x32_bf16 v[68:71], v[110:113], v[80:83], v[68:71]
	s_waitcnt lgkmcnt(3)
	v_mfma_f32_16x16x32_bf16 v[56:59], v[118:121], v[80:83], v[56:59]
	s_waitcnt lgkmcnt(1)
	v_mfma_f32_16x16x32_bf16 v[16:19], v[140:143], v[80:83], v[16:19]
	v_mfma_f32_16x16x32_bf16 v[72:75], v[106:109], v[84:87], v[72:75]
	v_mfma_f32_16x16x32_bf16 v[68:71], v[114:117], v[84:87], v[68:71]
	v_mfma_f32_16x16x32_bf16 v[56:59], v[136:139], v[84:87], v[56:59]
	s_waitcnt lgkmcnt(0)
	v_mfma_f32_16x16x32_bf16 v[16:19], v[144:147], v[84:87], v[16:19]
	v_add_u32_e32 v94, 0xa800, v134
	ds_read_b128 v[90:93], v94 offset:1024
	ds_read_b128 v[106:109], v94 offset:1088
	v_add_u32_e32 v94, 0xb000, v134
	ds_read_b128 v[110:113], v94 offset:1280
	ds_read_b128 v[114:117], v94 offset:1344
	v_add_u32_e32 v94, 0xb800, v134
	ds_read_b128 v[118:121], v94 offset:1536
	ds_read_b128 v[136:139], v94 offset:1600
	v_add_u32_e32 v94, 0xc000, v134
	ds_read_b128 v[140:143], v94 offset:1792
	ds_read_b128 v[144:147], v94 offset:1856
	s_waitcnt lgkmcnt(7)
	v_mfma_f32_16x16x32_bf16 v[28:31], v[90:93], v[80:83], v[28:31]
	s_waitcnt lgkmcnt(5)
	v_mfma_f32_16x16x32_bf16 v[20:23], v[110:113], v[80:83], v[20:23]
	s_waitcnt lgkmcnt(3)
	v_mfma_f32_16x16x32_bf16 v[24:27], v[118:121], v[80:83], v[24:27]
	s_waitcnt lgkmcnt(1)
	v_mfma_f32_16x16x32_bf16 v[76:79], v[140:143], v[80:83], v[76:79]
	v_mfma_f32_16x16x32_bf16 v[28:31], v[106:109], v[84:87], v[28:31]
	v_mfma_f32_16x16x32_bf16 v[20:23], v[114:117], v[84:87], v[20:23]
	v_mfma_f32_16x16x32_bf16 v[24:27], v[136:139], v[84:87], v[24:27]
	s_waitcnt lgkmcnt(0)
	v_mfma_f32_16x16x32_bf16 v[76:79], v[144:147], v[84:87], v[76:79]
	v_add_f32_e32 v135, v135, v89
	s_andn2_b64 vcc, exec, s[76:77]
	s_add_i32 s39, s39, 1
	s_cbranch_vccz .LBB0_1072
	v_mov_b32_e32 v136, v88
	s_branch .LBB0_1056

.LBB0_1108:
	s_or_b64 exec, exec, s[4:5]
	v_mov_b32_e32 v0, s48
	s_waitcnt lgkmcnt(0)
	s_barrier
	ds_read_b32 v0, v0
	s_mov_b64 s[4:5], -1
	s_waitcnt lgkmcnt(0)
	v_cmp_lt_i32_e32 vcc, 63, v0
	v_readfirstlane_b32 s6, v0
	s_cbranch_vccnz .LBB0_1101
	s_mov_b64 s[82:83], s[0:1]
	v_mov_b32_e32 v100, v226
	s_load_dwordx2 s[56:57], s[82:83], 0x58
	s_lshl_b32 s5, s6, 1
	s_and_b32 s4, s6, 1
	s_and_b32 s5, s5, -4
	s_sub_i32 s5, 0x7c, s5
	s_or_b32 s6, s4, s38
	s_waitcnt lgkmcnt(0)
	s_add_u32 s80, s56, 0xb400000
	v_readfirstlane_b32 s4, v100
	s_addc_u32 s81, s57, 0
	s_ashr_i32 s7, s4, 8
	s_lshl_b32 s22, s6, 1
	s_bfe_u32 s9, s5, 0x50002
	s_add_i32 s8, s7, s22
	s_lshl_b32 s5, s5, 4
	v_and_b32_e32 v28, 15, v100
	s_or_b32 s5, s5, s39
	s_lshr_b32 s4, s4, 2
	s_lshl_b32 s8, s8, 7
	s_and_b32 s23, s5, 0xfffff800
	s_lshl_b32 s5, s9, 6
	v_and_or_b32 v127, s4, 48, v28
	s_add_i32 s4, s8, 0x800
	s_or_b32 s5, s5, s23
	s_ashr_i32 s4, s4, 7
	v_or_b32_e32 v96, s5, v127
	s_ashr_i32 s5, s4, 31
	s_lshl_b64 s[4:5], s[4:5], 21
	v_ashrrev_i32_e32 v18, 5, v100
	v_ashrrev_i32_e32 v97, 31, v96
	s_add_u32 s4, s80, s4
	v_add_u32_e32 v16, s23, v18
	v_bfe_u32 v29, v100, 4, 2
	s_addc_u32 s5, s81, s5
	v_lshlrev_b64 v[98:99], 8, v[96:97]
	v_ashrrev_i32_e32 v17, 31, v16
	v_lshl_add_u64 v[0:1], s[4:5], 0, v[98:99]
	v_lshlrev_b32_e32 v208, 4, v29
	v_and_b32_e32 v19, 16, v100
	v_lshlrev_b64 v[16:17], 8, v[16:17]
	s_lshl_b32 s4, s6, 22
	v_lshl_add_u64 v[12:13], v[0:1], 0, v[208:209]
	v_lshl_add_u64 v[16:17], s[80:81], 0, v[16:17]
	v_lshl_or_b32 v208, v19, 17, s4
	v_lshlrev_b32_e32 v19, 4, v100
	v_lshl_add_u64 v[16:17], v[16:17], 0, v[208:209]
	v_and_b32_e32 v208, 0xf0, v19
	v_lshl_add_u64 v[16:17], v[16:17], 0, v[208:209]
	v_ashrrev_i32_e32 v19, 3, v100
	s_ashr_i32 s4, s23, 6
	v_lshl_add_u64 v[102:103], v[16:17], 0, s[62:63]
	v_lshl_add_u32 v16, s6, 8, v19
	s_ashr_i32 s5, s4, 31
	v_add_u32_e32 v16, 0x400, v16
	s_lshl_b64 s[4:5], s[4:5], 18
	v_lshlrev_b32_e32 v21, 3, v100
	v_ashrrev_i32_e32 v17, 31, v16
	s_add_u32 s4, s56, s4
	v_and_b32_e32 v22, 56, v21
	s_addc_u32 s5, s57, s5
	v_lshlrev_b64 v[16:17], 7, v[16:17]
	v_lshl_add_u64 v[16:17], s[4:5], 0, v[16:17]
	v_lshlrev_b32_e32 v208, 1, v22
	v_lshl_add_u64 v[16:17], v[16:17], 0, v[208:209]
	v_lshl_add_u64 v[104:105], v[16:17], 0, s[64:65]
	v_mul_lo_u32 v16, v19, s49
	v_add_lshl_u32 v31, v16, v22, 1
	v_lshlrev_b32_e32 v16, 2, v100
	v_sub_u32_e64 v20, s9, 8 clamp
	v_and_b32_e32 v16, 64, v16
	v_add_u32_e32 v16, v16, v18
	v_lshlrev_b32_e32 v208, 18, v20
	v_mul_lo_u32 v56, v16, s28
	v_lshl_add_u64 v[16:17], v[104:105], 0, v[208:209]
	v_add_co_u32_e32 v18, vcc, s21, v16
	v_lshlrev_b32_e32 v208, 14, v20
	v_readfirstlane_b32 s40, v20
	v_and_b32_e32 v57, 0x78, v21
	v_addc_co_u32_e32 v19, vcc, 0, v17, vcc
	v_lshl_add_u64 v[20:21], v[102:103], 0, v[208:209]
	v_add_co_u32_e32 v22, vcc, s35, v20
	global_load_dwordx4 v[0:3], v[12:13], off
	global_load_dwordx4 v[4:7], v[12:13], off offset:64
	global_load_dwordx4 v[8:11], v[12:13], off offset:128
	s_nop 0
	global_load_dwordx4 v[12:15], v[12:13], off offset:192
	v_addc_co_u32_e32 v23, vcc, 0, v21, vcc
	v_add_co_u32_e32 v24, vcc, s20, v16
	s_mul_i32 s4, s7, 0x410
	s_nop 0
	v_addc_co_u32_e32 v25, vcc, 0, v17, vcc
	v_add_co_u32_e32 v26, vcc, s17, v20
	s_add_i32 s41, s4, 0
	s_nop 0
	v_addc_co_u32_e32 v27, vcc, 0, v21, vcc
	global_load_dwordx4 v[52:55], v[24:25], off
	global_load_dwordx4 v[48:51], v[26:27], off
	v_add_co_u32_e32 v24, vcc, s17, v16
	v_lshlrev_b32_e32 v30, 3, v29
	s_nop 0
	v_addc_co_u32_e32 v25, vcc, 0, v17, vcc
	v_add_co_u32_e32 v26, vcc, s34, v20
	s_or_b32 s84, s12, s22
	s_nop 0
	v_addc_co_u32_e32 v27, vcc, 0, v21, vcc
	global_load_dwordx4 v[44:47], v[24:25], off
	global_load_dwordx4 v[40:43], v[26:27], off
	global_load_dwordx4 v[64:67], v[18:19], off
	global_load_dwordx4 v[32:35], v[16:17], off
	global_load_dwordx4 v[60:63], v[22:23], off
	global_load_dwordx4 v[36:39], v[20:21], off
	v_and_b32_e32 v19, 64, v233
	v_xor_b32_e32 v18, 16, v233
	v_add_u32_e32 v19, 64, v19
	v_cmp_lt_i32_e64 s[4:5], v18, v19
	v_max_i32_e32 v20, 2, v100
	v_sub_u32_e32 v20, v20, v100
	v_cndmask_b32_e64 v18, v233, v18, s[4:5]
	v_lshlrev_b32_e32 v126, 2, v18
	v_xor_b32_e32 v18, 32, v233
	v_cmp_lt_i32_e64 s[4:5], v18, v19
	v_add_u32_e32 v20, 0x1ff, v20
	v_lshl_or_b32 v17, s7, 6, v28
	v_cndmask_b32_e64 v18, v233, v18, s[4:5]
	v_lshrrev_b32_e32 v21, 9, v20
	v_mul_lo_u32 v17, v17, s28
	v_lshlrev_b32_e32 v125, 2, v18
	v_lshl_or_b32 v18, s7, 7, v28
	v_add_u32_e32 v21, 1, v21
	v_add_lshl_u32 v16, v56, v57, 1
	v_cmp_lt_i32_e32 vcc, s24, v100
	v_add_lshl_u32 v17, v17, v30, 1
	v_mul_lo_u32 v18, v18, s16
	v_add_u32_e32 v19, 0, v30
	v_lshlrev_b32_e32 v208, 2, v29
	v_and_b32_e32 v129, 0xfffffe, v21
	v_mov_b32_e32 v135, 0
	s_mov_b32 s43, s76
	s_add_i32 s41, s41, 0x16000
	s_mov_b32 s85, s13
	v_not_b32_e32 v128, v208
	v_or_b32_e32 v124, 16, v208
	v_or_b32_e32 v123, 32, v208
	v_or_b32_e32 v122, 48, v208
	v_cmp_lt_u32_e64 s[4:5], s61, v20
	v_lshl_add_u32 v130, v129, 9, v100
	s_mov_b32 s86, s84
	s_mov_b32 s87, s13
	s_mov_b32 s88, s84
	s_mov_b32 s89, s13
	v_add_u32_e32 v101, 0x200, v100
	v_cmp_ne_u32_e64 s[6:7], v21, v129
	v_mov_b32_e32 v136, 0xf149f2ca
	v_add_u32_e32 v131, 0, v16
	v_add_u32_e32 v132, 0, v31
	s_xor_b64 s[90:91], vcc, -1
	v_add_u32_e32 v133, 0, v17
	v_add_u32_e32 v134, v19, v18
	v_and_b32_e32 v149, 15, v100
	v_add_u32_e32 v149, 4, v149
	v_bfe_u32 v149, v149, 3, 1
	v_bfe_u32 v150, v100, 4, 2
	v_xor_b32_e32 v151, v150, v149
	v_lshlrev_b32_e32 v151, 4, v151
	v_lshlrev_b32_e32 v150, 3, v150
	v_sub_u32_e32 v151, v151, v150
	v_add_u32_e32 v134, v134, v151
	v_and_b32_e32 v149, 7, v100
	v_lshlrev_b32_e32 v150, 4, v149
	v_sub_u32_e32 v132, v132, v150
	v_and_b32_e32 v150, 4, v149
	v_lshl_add_u32 v132, v150, 4, v132
	v_and_b32_e32 v150, 1, v149
	v_lshl_add_u32 v132, v150, 5, v132
	v_and_b32_e32 v150, 2, v149
	v_lshl_add_u32 v132, v150, 2, v132
	v_bfe_u32 v150, v100, 3, 4
	v_add_u32_e32 v150, 4, v150
	v_bfe_u32 v150, v150, 3, 1
	v_lshlrev_b32_e32 v150, 4, v150
	v_sub_u32_e32 v148, 16, v150
	v_add_u32_e32 v148, v148, v132
	v_add_u32_e32 v132, v132, v150
	s_mov_b32 s42, s40
	v_mov_b32_e32 v20, 0
	v_mov_b32_e32 v21, v135
	v_mov_b32_e32 v22, v135
	v_mov_b32_e32 v23, v135
	v_mov_b32_e32 v28, 0
	v_mov_b32_e32 v29, v135
	v_mov_b32_e32 v30, v135
	v_mov_b32_e32 v31, v135
	v_mov_b32_e32 v16, 0
	v_mov_b32_e32 v17, v135
	v_mov_b32_e32 v18, v135
	v_mov_b32_e32 v19, v135
	v_mov_b32_e32 v56, 0
	v_mov_b32_e32 v57, v135
	v_mov_b32_e32 v58, v135
	v_mov_b32_e32 v59, v135
	v_mov_b32_e32 v68, 0
	v_mov_b32_e32 v69, v135
	v_mov_b32_e32 v70, v135
	v_mov_b32_e32 v71, v135
	v_mov_b32_e32 v72, 0
	v_mov_b32_e32 v73, v135
	v_mov_b32_e32 v74, v135
	v_mov_b32_e32 v75, v135
	v_mov_b32_e32 v24, 0
	v_mov_b32_e32 v25, v135
	v_mov_b32_e32 v26, v135
	v_mov_b32_e32 v27, v135
	v_mov_b32_e32 v76, 0
	v_mov_b32_e32 v77, v135
	v_mov_b32_e32 v78, v135
	v_mov_b32_e32 v79, v135
.LBB0_1110:
	s_cmp_eq_u32 s42, s40
	s_cselect_b64 s[22:23], -1, 0
	s_and_b64 s[22:23], s[90:91], s[22:23]
	s_barrier
	s_waitcnt vmcnt(0)
	ds_write_b128 v131, v[36:39]
	ds_write_b64 v132, v[32:33] offset:34816
	ds_write_b64 v148, v[34:35] offset:34816
	ds_write_b128 v131, v[40:43] offset:4352
	ds_write_b64 v132, v[44:45] offset:44032
	ds_write_b64 v148, v[46:47] offset:44032
	ds_write_b128 v131, v[48:51] offset:8704
	ds_write_b64 v132, v[52:53] offset:53248
	ds_write_b64 v148, v[54:55] offset:53248
	ds_write_b128 v131, v[60:63] offset:13056
	ds_write_b64 v132, v[64:65] offset:62464
	ds_write_b64 v148, v[66:67] offset:62464
	s_and_saveexec_b64 s[76:77], s[22:23]
	s_cbranch_execz .LBB0_1118
	s_load_dwordx2 s[92:93], s[82:83], 0x48
	s_mov_b64 s[22:23], -1
	v_mov_b32_e32 v80, v100
	s_and_saveexec_b64 s[94:95], s[4:5]
	s_cbranch_execz .LBB0_1115
	s_mov_b64 s[96:97], 0
	v_mov_b32_e32 v82, v129
	v_mov_b64_e32 v[80:81], v[100:101]

.LBB0_1124:
	s_nop 1
	ds_bpermute_b32 v80, v126, v137
	v_max_f32_e32 v81, v137, v137
	s_waitcnt lgkmcnt(0)
	v_max_f32_e32 v80, v80, v80
	v_max_f32_e32 v80, v81, v80
	ds_bpermute_b32 v81, v125, v80
	s_waitcnt lgkmcnt(0)
	v_max3_f32 v88, v136, v80, v81
	v_sub_f32_e32 v80, v136, v88
	v_exp_f32_e32 v90, v80
	v_sub_f32_e32 v80, v120, v88
	v_exp_f32_e32 v80, v80
	v_sub_f32_e32 v82, v121, v88
	v_exp_f32_e32 v82, v82
	v_sub_f32_e32 v83, v112, v88
	v_exp_f32_e32 v83, v83
	v_sub_f32_e32 v84, v113, v88
	v_exp_f32_e32 v84, v84
	v_sub_f32_e32 v85, v108, v88
	v_fma_f32 v81, v135, v90, v80
	v_exp_f32_e32 v85, v85
	v_sub_f32_e32 v86, v109, v88
	v_add_f32_e32 v81, v82, v81
	v_exp_f32_e32 v86, v86
	v_sub_f32_e32 v87, v106, v88
	v_add_f32_e32 v81, v83, v81
	v_exp_f32_e32 v87, v87
	v_sub_f32_e32 v89, v107, v88
	v_add_f32_e32 v81, v84, v81
	v_exp_f32_e32 v89, v89
	v_add_f32_e32 v81, v85, v81
	v_add_f32_e32 v81, v86, v81
	v_add_f32_e32 v81, v87, v81
	v_add_f32_e32 v91, v89, v81
	v_cvt_pk_bf16_f32 v81, v83, v84
	v_sub_f32_e32 v84, v110, v88
	v_cvt_pk_bf16_f32 v83, v87, v89
	v_exp_f32_e32 v89, v84
	v_sub_f32_e32 v84, v111, v88
	v_exp_f32_e32 v92, v84
	v_sub_f32_e32 v84, v114, v88
	v_exp_f32_e32 v93, v84
	v_sub_f32_e32 v84, v115, v88
	v_exp_f32_e32 v94, v84
	v_sub_f32_e32 v84, v116, v88
	v_exp_f32_e32 v95, v84
	v_sub_f32_e32 v84, v117, v88
	v_exp_f32_e32 v106, v84
	v_sub_f32_e32 v84, v118, v88
	v_exp_f32_e32 v107, v84
	v_sub_f32_e32 v84, v119, v88
	v_exp_f32_e32 v135, v84
	v_cvt_pk_bf16_f32 v84, v89, v92
	v_add_f32_e32 v89, v89, v91
	v_add_f32_e32 v89, v92, v89
	v_add_f32_e32 v89, v93, v89
	v_add_f32_e32 v89, v94, v89
	v_add_f32_e32 v89, v95, v89
	v_cvt_pk_bf16_f32 v80, v80, v82
	v_cvt_pk_bf16_f32 v82, v85, v86
	v_cvt_pk_bf16_f32 v85, v93, v94
	v_add_f32_e32 v89, v106, v89
	v_add_u32_e32 v94, 0x8800, v134
	v_cvt_pk_bf16_f32 v86, v95, v106
	v_cvt_pk_bf16_f32 v87, v107, v135
	v_pk_mul_f32 v[74:75], v[74:75], v[90:91] op_sel_hi:[1,0]
	v_pk_mul_f32 v[72:73], v[72:73], v[90:91] op_sel_hi:[1,0]
	v_pk_mul_f32 v[70:71], v[70:71], v[90:91] op_sel_hi:[1,0]
	v_pk_mul_f32 v[68:69], v[68:69], v[90:91] op_sel_hi:[1,0]
	v_pk_mul_f32 v[58:59], v[58:59], v[90:91] op_sel_hi:[1,0]
	v_pk_mul_f32 v[56:57], v[56:57], v[90:91] op_sel_hi:[1,0]
	v_pk_mul_f32 v[18:19], v[18:19], v[90:91] op_sel_hi:[1,0]
	v_pk_mul_f32 v[16:17], v[16:17], v[90:91] op_sel_hi:[1,0]
	v_pk_mul_f32 v[30:31], v[30:31], v[90:91] op_sel_hi:[1,0]
	v_pk_mul_f32 v[28:29], v[28:29], v[90:91] op_sel_hi:[1,0]
	v_pk_mul_f32 v[22:23], v[22:23], v[90:91] op_sel_hi:[1,0]
	v_pk_mul_f32 v[20:21], v[20:21], v[90:91] op_sel_hi:[1,0]
	v_pk_mul_f32 v[26:27], v[26:27], v[90:91] op_sel_hi:[1,0]
	v_pk_mul_f32 v[24:25], v[24:25], v[90:91] op_sel_hi:[1,0]
	v_pk_mul_f32 v[78:79], v[78:79], v[90:91] op_sel_hi:[1,0]
	v_pk_mul_f32 v[76:77], v[76:77], v[90:91] op_sel_hi:[1,0]
	v_add_f32_e32 v89, v107, v89
	ds_read_b128 v[90:93], v94
	ds_read_b128 v[106:109], v94 offset:64
	v_add_u32_e32 v94, 0x9000, v134
	ds_read_b128 v[110:113], v94 offset:256
	ds_read_b128 v[114:117], v94 offset:320
	v_add_u32_e32 v94, 0x9800, v134
	ds_read_b128 v[118:121], v94 offset:512
	ds_read_b128 v[136:139], v94 offset:576
	v_add_u32_e32 v94, 0xa000, v134
	ds_read_b128 v[140:143], v94 offset:768
	ds_read_b128 v[144:147], v94 offset:832
	s_waitcnt lgkmcnt(7)
	v_mfma_f32_16x16x32_bf16 v[72:75], v[90:93], v[80:83], v[72:75]
	s_waitcnt lgkmcnt(5)
	v_mfma_f32_16x16x32_bf16 v[68:71], v[110:113], v[80:83], v[68:71]
	s_waitcnt lgkmcnt(3)
	v_mfma_f32_16x16x32_bf16 v[56:59], v[118:121], v[80:83], v[56:59]
	s_waitcnt lgkmcnt(1)
	v_mfma_f32_16x16x32_bf16 v[16:19], v[140:143], v[80:83], v[16:19]
	v_mfma_f32_16x16x32_bf16 v[72:75], v[106:109], v[84:87], v[72:75]
	v_mfma_f32_16x16x32_bf16 v[68:71], v[114:117], v[84:87], v[68:71]
	v_mfma_f32_16x16x32_bf16 v[56:59], v[136:139], v[84:87], v[56:59]
	s_waitcnt lgkmcnt(0)
	v_mfma_f32_16x16x32_bf16 v[16:19], v[144:147], v[84:87], v[16:19]
	v_add_u32_e32 v94, 0xa800, v134
	ds_read_b128 v[90:93], v94 offset:1024
	ds_read_b128 v[106:109], v94 offset:1088
	v_add_u32_e32 v94, 0xb000, v134
	ds_read_b128 v[110:113], v94 offset:1280
	ds_read_b128 v[114:117], v94 offset:1344
	v_add_u32_e32 v94, 0xb800, v134
	ds_read_b128 v[118:121], v94 offset:1536
	ds_read_b128 v[136:139], v94 offset:1600
	v_add_u32_e32 v94, 0xc000, v134
	ds_read_b128 v[140:143], v94 offset:1792
	ds_read_b128 v[144:147], v94 offset:1856
	s_waitcnt lgkmcnt(7)
	v_mfma_f32_16x16x32_bf16 v[28:31], v[90:93], v[80:83], v[28:31]
	s_waitcnt lgkmcnt(5)
	v_mfma_f32_16x16x32_bf16 v[20:23], v[110:113], v[80:83], v[20:23]
	s_waitcnt lgkmcnt(3)
	v_mfma_f32_16x16x32_bf16 v[24:27], v[118:121], v[80:83], v[24:27]
	s_waitcnt lgkmcnt(1)
	v_mfma_f32_16x16x32_bf16 v[76:79], v[140:143], v[80:83], v[76:79]
	v_mfma_f32_16x16x32_bf16 v[28:31], v[106:109], v[84:87], v[28:31]
	v_mfma_f32_16x16x32_bf16 v[20:23], v[114:117], v[84:87], v[20:23]
	v_mfma_f32_16x16x32_bf16 v[24:27], v[136:139], v[84:87], v[24:27]
	s_waitcnt lgkmcnt(0)
	v_mfma_f32_16x16x32_bf16 v[76:79], v[144:147], v[84:87], v[76:79]
	v_add_f32_e32 v135, v135, v89
	s_andn2_b64 vcc, exec, s[76:77]
	s_add_i32 s42, s42, 1
	s_cbranch_vccz .LBB0_1100
	v_mov_b32_e32 v136, v88
	s_branch .LBB0_1110
